# FN 13,16 with the wave-half alignment barrier moved to the start of the fused epilogue (both halves load and update x concurrently)
# speedup vs baseline: 1.0203x; 1.0203x over previous
; #define GAS __attribute__((address_space(1)))
; __device__ __forceinline__ void gemm_epilogue(LAS unsigned char* lds, const GD& gd, const f32x4 (&acc)[2][2][4][2], const Unit& u) {
;     ...
; #pragma unroll
;         for (int am = 0; am < 8 / MBR; ++am) {
;             const int ai = (am * MBR) >> 2, m0 = (am * MBR) & 3;
;             f32x4 xi[MBR][2][2];
; #pragma unroll
;             for (int mm = 0; mm < MBR; ++mm)
; #pragma unroll
;                 for (int bj = 0; bj < 2; ++bj)
; #pragma unroll
;                     for (int n = 0; n < 2; ++n) xi[mm][bj][n] = *(GAS const f32x4*)(xin + xoff + (ai * HALF + (m0 + mm) * 16) * DM + bj * HALF + n * 16);
;             asm volatile("" ::: "memory");
; #pragma unroll
;             for (int mm = 0; mm < MBR; ++mm)
; #pragma unroll
;                 for (int bj = 0; bj < 2; ++bj)
; #pragma unroll
;                     for (int n = 0; n < 2; ++n) *(GAS f32x4*)(xout + xoff + (ai * HALF + (m0 + mm) * 16) * DM + bj * HALF + n * 16) = xi[mm][bj][n] + gv[bj][n] * acc[ai][bj][m0 + mm][n];
;         }
.Lmy_fn_go:
	s_cmp_lg_u32 s98, 0
	s_cbranch_scc1 .Lmy_fn_e0
	s_barrier

; __device__ void phase_norm(const Params& p, int l, int which) {
;     ...
;         float s = 0.f;
; #pragma unroll
;         for (int j = 0; j < 4; ++j) s += (v[j].x * v[j].x + v[j].y * v[j].y) + (v[j].z * v[j].z + v[j].w * v[j].w);
;         const float rstd = rsqrtf(wave_sum(s) * (1.f / 1024.f) + 1e-6f);
.Lmy_fn_ns3:
	v_pk_mul_f32 v[192:193], v[126:127], v[126:127]
	v_pk_fma_f32 v[192:193], v[128:129], v[128:129], v[192:193]
	v_pk_fma_f32 v[192:193], v[4:5], v[4:5], v[192:193]
	v_pk_fma_f32 v[192:193], v[6:7], v[6:7], v[192:193]
	v_pk_fma_f32 v[192:193], v[48:49], v[48:49], v[192:193]
	v_pk_fma_f32 v[192:193], v[50:51], v[50:51], v[192:193]
	v_pk_fma_f32 v[192:193], v[12:13], v[12:13], v[192:193]
	v_pk_fma_f32 v[192:193], v[14:15], v[14:15], v[192:193]
	v_add_f32_e32 v184, v192, v193
	v_pk_mul_f32 v[192:193], v[122:123], v[122:123]
	v_pk_fma_f32 v[192:193], v[124:125], v[124:125], v[192:193]
	v_pk_fma_f32 v[192:193], v[118:119], v[118:119], v[192:193]
	v_pk_fma_f32 v[192:193], v[120:121], v[120:121], v[192:193]
	v_pk_fma_f32 v[192:193], v[102:103], v[102:103], v[192:193]
	v_pk_fma_f32 v[192:193], v[104:105], v[104:105], v[192:193]
	v_pk_fma_f32 v[192:193], v[98:99], v[98:99], v[192:193]
	v_pk_fma_f32 v[192:193], v[100:101], v[100:101], v[192:193]
	v_add_f32_e32 v185, v192, v193
	v_pk_mul_f32 v[192:193], v[114:115], v[114:115]
	v_pk_fma_f32 v[192:193], v[116:117], v[116:117], v[192:193]
	v_pk_fma_f32 v[192:193], v[110:111], v[110:111], v[192:193]
	v_pk_fma_f32 v[192:193], v[112:113], v[112:113], v[192:193]
	v_pk_fma_f32 v[192:193], v[92:93], v[92:93], v[192:193]
	v_pk_fma_f32 v[192:193], v[94:95], v[94:95], v[192:193]
	v_pk_fma_f32 v[192:193], v[88:89], v[88:89], v[192:193]
	v_pk_fma_f32 v[192:193], v[90:91], v[90:91], v[192:193]
	v_add_f32_e32 v186, v192, v193
	v_pk_mul_f32 v[192:193], v[106:107], v[106:107]
	v_pk_fma_f32 v[192:193], v[108:109], v[108:109], v[192:193]
	v_pk_fma_f32 v[192:193], v[8:9], v[8:9], v[192:193]
	v_pk_fma_f32 v[192:193], v[10:11], v[10:11], v[192:193]
	v_pk_fma_f32 v[192:193], v[44:45], v[44:45], v[192:193]
	v_pk_fma_f32 v[192:193], v[46:47], v[46:47], v[192:193]
	v_pk_fma_f32 v[192:193], v[16:17], v[16:17], v[192:193]
	v_pk_fma_f32 v[192:193], v[18:19], v[18:19], v[192:193]
	v_add_f32_e32 v187, v192, v193
	v_pk_mul_f32 v[192:193], v[84:85], v[84:85]
	v_pk_fma_f32 v[192:193], v[86:87], v[86:87], v[192:193]
	v_pk_fma_f32 v[192:193], v[20:21], v[20:21], v[192:193]
	v_pk_fma_f32 v[192:193], v[22:23], v[22:23], v[192:193]
	v_pk_fma_f32 v[192:193], v[40:41], v[40:41], v[192:193]
	v_pk_fma_f32 v[192:193], v[42:43], v[42:43], v[192:193]
	v_pk_fma_f32 v[192:193], v[28:29], v[28:29], v[192:193]
	v_pk_fma_f32 v[192:193], v[30:31], v[30:31], v[192:193]
	v_add_f32_e32 v188, v192, v193
	v_pk_mul_f32 v[192:193], v[80:81], v[80:81]
	v_pk_fma_f32 v[192:193], v[82:83], v[82:83], v[192:193]
	v_pk_fma_f32 v[192:193], v[76:77], v[76:77], v[192:193]
	v_pk_fma_f32 v[192:193], v[78:79], v[78:79], v[192:193]
	v_pk_fma_f32 v[192:193], v[60:61], v[60:61], v[192:193]
	v_pk_fma_f32 v[192:193], v[62:63], v[62:63], v[192:193]
	v_pk_fma_f32 v[192:193], v[56:57], v[56:57], v[192:193]
	v_pk_fma_f32 v[192:193], v[58:59], v[58:59], v[192:193]
	v_add_f32_e32 v189, v192, v193
	v_pk_mul_f32 v[192:193], v[72:73], v[72:73]
	v_pk_fma_f32 v[192:193], v[74:75], v[74:75], v[192:193]
	v_pk_fma_f32 v[192:193], v[68:69], v[68:69], v[192:193]
	v_pk_fma_f32 v[192:193], v[70:71], v[70:71], v[192:193]
	v_pk_fma_f32 v[192:193], v[52:53], v[52:53], v[192:193]
	v_pk_fma_f32 v[192:193], v[54:55], v[54:55], v[192:193]
	v_pk_fma_f32 v[192:193], v[0:1], v[0:1], v[192:193]
	v_pk_fma_f32 v[192:193], v[2:3], v[2:3], v[192:193]
	v_add_f32_e32 v190, v192, v193
	v_pk_mul_f32 v[192:193], v[64:65], v[64:65]
	v_pk_fma_f32 v[192:193], v[66:67], v[66:67], v[192:193]
	v_pk_fma_f32 v[192:193], v[24:25], v[24:25], v[192:193]
	v_pk_fma_f32 v[192:193], v[26:27], v[26:27], v[192:193]
	v_pk_fma_f32 v[192:193], v[36:37], v[36:37], v[192:193]
	v_pk_fma_f32 v[192:193], v[38:39], v[38:39], v[192:193]
	v_pk_fma_f32 v[192:193], v[32:33], v[32:33], v[192:193]
	v_pk_fma_f32 v[192:193], v[34:35], v[34:35], v[192:193]
	v_add_f32_e32 v191, v192, v193
	v_lshl_or_b32 v198, s98, 6, v252
	v_lshlrev_b32_e32 v194, 6, v198
	v_lshl_add_u32 v194, v251, 4, v194
	s_lshl_b32 s2, s15, 2
	s_add_i32 s2, s2, 0x20000
	v_add_u32_e32 v194, s2, v194
	ds_write_b32 v194, v184
	ds_write_b32 v194, v185 offset:1024
	ds_write_b32 v194, v186 offset:2048
	ds_write_b32 v194, v187 offset:3072
	ds_write_b32 v194, v188 offset:8192
	ds_write_b32 v194, v189 offset:9216
	ds_write_b32 v194, v190 offset:10240
	ds_write_b32 v194, v191 offset:11264
	s_waitcnt lgkmcnt(0)
	s_barrier
	s_cmp_lg_u32 s98, 0
	s_cbranch_scc1 .Lmy_fn_b1
	v_mov_b32_e32 v195, 0x240a8
	ds_read_b64 v[196:197], v195
	v_lshlrev_b32_e32 v194, 6, v210
	v_add_u32_e32 v194, 0x20000, v194
	ds_read_b128 v[152:155], v194
	ds_read_b128 v[156:159], v194 offset:16
	ds_read_b128 v[160:163], v194 offset:32
	ds_read_b128 v[164:167], v194 offset:48
	s_waitcnt lgkmcnt(0)
	v_readfirstlane_b32 s48, v196
	v_readfirstlane_b32 s49, v197
	v_add_f32_e32 v192, v152, v153
	v_add_f32_e32 v192, v192, v154
	v_add_f32_e32 v192, v192, v155
	v_add_f32_e32 v192, v192, v156
	v_add_f32_e32 v192, v192, v157
	v_add_f32_e32 v192, v192, v158
	v_add_f32_e32 v192, v192, v159
	v_add_f32_e32 v192, v192, v160
	v_add_f32_e32 v192, v192, v161
	v_add_f32_e32 v192, v192, v162
	v_add_f32_e32 v192, v192, v163
	v_add_f32_e32 v192, v192, v164
	v_add_f32_e32 v192, v192, v165
	v_add_f32_e32 v192, v192, v166
	v_add_f32_e32 v192, v192, v167
	s_add_u32 s50, s48, 0x100100
	s_addc_u32 s51, s49, 0
	s_cmp_lt_u32 s33, 64
	s_cbranch_scc1 .Lmy_fn_lat
	s_sub_u32 s50, s50, 0x1d0
	s_subb_u32 s51, s51, 0
